# UQKV: rotate kv-GEMM block->unit map so its 8 double-unit blocks are ones idle in the q GEMM
# speedup vs baseline: 1.0090x; 1.0090x over previous
;   __host__ __device__ __forceinline__ float* RS() const { return (float*)(wsl() + OFF_RS); }
;   __host__ __device__ __forceinline__ bf16_t* Wuq() const { return (bf16_t*)(wsl() + OFF_WUQ); }
;   __host__ __device__ __forceinline__ bf16_t* Wukv() const { return (bf16_t*)(wsl() + OFF_WUKV); }
;   __host__ __device__ __forceinline__ bf16_t* ACT() const { return (bf16_t*)(wsl() + OFF_ACT); }
;   __host__ __device__ __forceinline__ bf16_t* R() const { return (bf16_t*)(wsl() + OFF_R); }
; __device__ __forceinline__ int obid() { int t = blockIdx.x; asm volatile("" : "+s"(t)); return t; }
; template <int KIND>
; __device__ __forceinline__ void fast_gemm(const Params& p, FEpi e, const bf16_t* A, int lda, const bf16_t* Bt, int K, int nN, int latent, char* smem) {
;   pg8::Sched S; S.init(latent ? 64 : 66, nN, gridDim.x, obid(), latent);
; __device__ __forceinline__ void run_phase(const Params& p, int ph, char* smem) {
;     ...
;     case K_UQKV: if (!KEN(K_UQKV)) break;
;       for (int q = 0; q < 2; ++q) {
;         fe.outb = q ? p.R() + (size_t)NTOK * 768 : p.R(); fe.ldo = q ? 1024 : 768; fe.rs = p.RS() + q;
;         fast_gemm<EPI_ROWSCALE>(p, fe, p.ACT() + (q ? 384 : 0), PW, q ? p.Wukv() : p.Wuq(), q ? 256 : 384, q ? 4 : 3, 0, smem);
;       }
.LBB0_454:
	s_and_b64 s[2:3], s[48:49], exec
	s_cselect_b32 s4, 3, 4
	s_mov_b32 s16, s82
	s_cbranch_scc1 .Luq_first
	s_sub_i32 s2, s80, 0xc6
	s_max_i32 s2, s2, 0
	s_add_i32 s16, s16, s2
	s_cmp_ge_u32 s16, s80
	s_cselect_b32 s2, s80, 0
	s_sub_i32 s16, s16, s2
.Luq_first:
	s_mul_i32 s30, s4, 0x42
	v_mov_b32_e32 v20, v164
	s_cmp_ge_i32 s16, s30
	v_readfirstlane_b32 s17, v20
	s_cbranch_scc1 .LBB0_453
	s_ashr_i32 s21, s16, 31
	s_lshr_b32 s2, s21, 29
	s_add_i32 s6, s16, s2
	s_lshr_b32 s19, s30, 3
	s_and_b32 s2, s6, -8
	s_and_b32 s20, s30, 6
	s_sub_i32 s7, s16, s2
	s_add_i32 s22, s19, 1
	s_cmp_ge_i32 s7, s20
	s_mov_b64 s[2:3], -1
	s_mul_i32 s23, s22, s20
	s_cbranch_scc0 .LBB0_457
	s_sub_i32 s2, s7, s20
	s_mul_i32 s2, s2, s19
	s_add_i32 s5, s2, s23
	s_mov_b64 s[2:3], 0
